# P7-start guard (teams pm >= 32 wait for two other teams' P5|P6 seam counters, two sequential round trips) pre-checked inside the P6|P7 seam's first poll round trip
# baseline (speedup 1.0000x reference)
; __device__ __forceinline__ unsigned xb_ld(unsigned* p)              { return __hip_atomic_load(p, __ATOMIC_RELAXED, __HIP_MEMORY_SCOPE_AGENT); }
; __device__ __forceinline__ unsigned xb_add(unsigned* p, unsigned v) { return __hip_atomic_fetch_add(p, v, __ATOMIC_RELAXED, __HIP_MEMORY_SCOPE_AGENT); }
; #define XB_SPIN(cond, bar) do { unsigned _sp = 0; while (cond) { __builtin_amdgcn_s_sleep(1); \
;     if ((++_sp & 255u) == 0u) { if (xb_ld(&(bar)[XB_TMO])) break; if (_sp > XB_SPIN_CAP) { atomicAdd(&(bar)[XB_TMO], 1u); break; } } } } while (0)
; __device__ __forceinline__ void team_barrier(unsigned* ctr, unsigned target, unsigned* bar) {
;     asm volatile("s_waitcnt vmcnt(0)" ::: "memory");
;     __syncthreads();
;     if (threadIdx.x == 0) {
;         __builtin_amdgcn_s_waitcnt(0);
;         (void)xb_add(ctr, 1u);
;         asm volatile("buffer_inv sc1" ::: "memory");
;         XB_SPIN(xb_ld(ctr) < target, bar);
;         asm volatile("s_waitcnt vmcnt(0)" ::: "memory");
;     }
;     __syncthreads();
; }
; __global__ void __launch_bounds__(NWAVES * 64, 2) fwd(Args args) {
;     ...
;         if (MISC[10] != 0u && team_pm >= 32) { if (tid == 0) { const int q_ = 2 * (team_pm - 32);
;                 XB_SPIN(xb_ld((unsigned*)(ctl + CW_TEAM) + 32 * q_) < 4u, bar.bar); XB_SPIN(xb_ld((unsigned*)(ctl + CW_TEAM) + 32 * (q_ + 1)) < 4u, bar.bar); }
.LBB0_1136:
	s_or_b64 exec, exec, s[10:11]
	buffer_inv sc1
	s_mov_b32 s101, 0
	v_mov_b32_e32 v4, 0
	v_mov_b32_e32 v5, 0
	s_cmp_lt_u32 s3, 32
	s_cbranch_scc1 .Lg7_skip
	s_lshl_b32 s5, s3, 8
	s_add_u32 s10, s60, s5
	s_addc_u32 s11, s61, 0
	v_mov_b32_e32 v3, 0x1e000
	global_load_dword v4, v3, s[10:11] sc1
	global_load_dword v5, v3, s[10:11] offset:128 sc1
.Lg7_skip:
	v_mov_b32_e32 v1, 0
	global_load_dword v2, v1, s[6:7] sc1
	s_waitcnt vmcnt(0)
	v_min_u32_e32 v4, v4, v5
	v_cmp_lt_u32_e32 vcc, 3, v4
	s_cbranch_vccz .Lg7_no
	s_mov_b32 s101, 1
.Lg7_no:
	v_cmp_lt_u32_e32 vcc, 3, v2
	s_cbranch_vccnz .LBB0_1150
	s_mov_b32 s5, 1
	s_branch .LBB0_1139

; __device__ __forceinline__ unsigned long long rt() { return __builtin_amdgcn_s_memrealtime(); }
; __device__ __forceinline__ unsigned xb_ld(unsigned* p)              { return __hip_atomic_load(p, __ATOMIC_RELAXED, __HIP_MEMORY_SCOPE_AGENT); }
; #define XB_SPIN(cond, bar) do { unsigned _sp = 0; while (cond) { __builtin_amdgcn_s_sleep(1); \
;     if ((++_sp & 255u) == 0u) { if (xb_ld(&(bar)[XB_TMO])) break; if (_sp > XB_SPIN_CAP) { atomicAdd(&(bar)[XB_TMO], 1u); break; } } } } while (0)
; __global__ void __launch_bounds__(NWAVES * 64, 2) fwd(Args args) {
;     ...
;     if (IN(7)) {
;         const unsigned long long amp_t0_7 = (PROBE_AMP == 7) ? rt() : 0ull;
;         if (MISC[10] != 0u && team_pm >= 32) { if (tid == 0) { const int q_ = 2 * (team_pm - 32);
;                 XB_SPIN(xb_ld((unsigned*)(ctl + CW_TEAM) + 32 * q_) < 4u, bar.bar); XB_SPIN(xb_ld((unsigned*)(ctl + CW_TEAM) + 32 * (q_ + 1)) < 4u, bar.bar); }
;             __syncthreads(); }
.LBB0_1201:
.LBB0_1202:
	s_cmp_lt_i32 s56, 8
	s_cselect_b64 s[0:1], -1, 0
	s_cmp_gt_i32 s57, 7
	s_cselect_b64 s[6:7], -1, 0
	s_and_b64 s[0:1], s[0:1], s[6:7]
	s_andn2_b64 vcc, exec, s[0:1]
	s_cbranch_vccnz .LBB0_1322
	s_add_i32 s0, 0, 0x22968
	s_waitcnt vmcnt(0)
	v_mov_b32_e32 v1, s0
	ds_read_b32 v1, v1
	s_cmp_gt_u32 s4, 31
	s_cselect_b64 s[0:1], -1, 0
	s_waitcnt lgkmcnt(0)
	v_cmp_ne_u32_e32 vcc, 0, v1
	s_and_b64 s[0:1], vcc, s[0:1]
	s_andn2_b64 vcc, exec, s[0:1]
	s_cbranch_vccnz .LBB0_1231
	s_and_saveexec_b64 s[0:1], s[96:97]
	s_cbranch_execz .LBB0_1230
	s_cmp_eq_u32 s101, 1
	s_cbranch_scc1 .LBB0_1230
	s_lshl_b32 s4, s3, 8
	s_add_u32 s6, s60, s4
	s_addc_u32 s7, s61, 0
	v_mov_b32_e32 v1, 0x1e000
	global_load_dword v1, v1, s[6:7] sc1
	s_add_u32 s4, s6, 0x20000
	s_addc_u32 s5, s7, 0
	s_add_u32 s6, s6, 0x1e000
	s_addc_u32 s7, s7, 0
	s_waitcnt vmcnt(0)
	v_cmp_lt_u32_e32 vcc, 3, v1
	s_cbranch_vccnz .LBB0_1218
	s_mov_b32 s18, 1
	v_mov_b32_e32 v1, 0
	s_branch .LBB0_1208
